# v51 + per-tile index math: rem/8 and rem%8 by shift/mask instead of the general software division (group size is always 8)
# baseline (speedup 1.0000x reference)
.LBB0_493:
	s_add_i32 s79, s79, 1
	s_mul_i32 s6, s79, s66
	s_mul_hi_u32 s7, s79, s33
	s_add_i32 s7, s7, s6
	s_mul_i32 s6, s79, s33
	s_add_u32 s14, s6, s2
	s_addc_u32 s15, s7, s3
	v_cmp_gt_i64_e32 vcc, s[14:15], v[146:147]
	v_cmp_lt_i64_e64 s[6:7], s[14:15], v[144:145]
	s_cbranch_vccnz .LBB0_495
	s_ashr_i32 s10, s14, 31
	s_lshr_b32 s10, s10, 29
	s_add_i32 s10, s14, s10
	s_ashr_i32 s11, s10, 3
	s_and_b32 s10, s10, -8
	s_sub_i32 s10, s14, s10
	s_cmp_lt_i32 s10, 0
	s_movk_i32 s12, 0x161
	s_cselect_b32 s12, s12, 0x160
	s_mul_i32 s10, s10, s12
	s_add_i32 s10, s10, s11
	s_mul_hi_i32 s11, s10, 0x2e8ba2e9
	s_lshr_b32 s12, s11, 31
	s_ashr_i32 s11, s11, 5
	s_add_i32 s11, s11, s12
	s_lshl_b32 s12, s11, 3
	s_sub_i32 s13, 0x80, s12
	s_min_i32 s13, s13, 8
	s_mulk_i32 s11, 0xb0
	s_sub_i32 s11, s10, s11
	s_lshr_b32 s10, s11, 3
	s_and_b32 s11, s11, 7
	s_add_i32 s12, s12, s11
	s_and_b32 s80, s79, 1

.LBB0_583:
	s_ashr_i32 s6, s14, 3
	s_add_i32 s6, s42, s6
	s_ashr_i32 s7, s6, 31
	s_lshr_b32 s7, s7, 27
	s_add_i32 s7, s6, s7
	s_ashr_i32 s14, s7, 5
	s_lshl_b32 s14, s14, 3
	s_sub_i32 s15, 0x80, s14
	s_min_i32 s15, s15, 8
	s_andn2_b32 s7, s7, 31
	s_sub_i32 s6, s6, s7
	s_lshr_b32 s70, s6, 3
	s_and_b32 s6, s6, 7
	s_add_i32 s71, s14, s6

.LBB0_681:
	s_add_i32 s65, s65, 1
	s_mul_i32 s5, s65, s96
	s_mul_hi_u32 s6, s65, s33
	s_add_i32 s6, s6, s5
	s_mul_i32 s5, s65, s33
	s_add_u32 s70, s5, s2
	s_addc_u32 s71, s6, s97
	v_cmp_gt_i64_e32 vcc, s[70:71], v[188:189]
	v_cmp_lt_i64_e64 s[6:7], s[70:71], v[186:187]
	s_cbranch_vccnz .LBB0_683
	s_ashr_i32 s4, s70, 31
	s_lshr_b32 s4, s4, 29
	s_add_i32 s4, s70, s4
	s_ashr_i32 s5, s4, 3
	s_and_b32 s4, s4, -8
	s_sub_i32 s4, s70, s4
	s_cmp_lt_i32 s4, 0
	s_movk_i32 s12, 0x51
	s_cselect_b32 s12, s12, 0x50
	s_mul_i32 s4, s4, s12
	s_add_i32 s4, s4, s5
	s_mul_hi_i32 s5, s4, 0x66666667
	s_lshr_b32 s12, s5, 31
	s_ashr_i32 s5, s5, 4
	s_add_i32 s5, s5, s12
	s_lshl_b32 s13, s5, 3
	s_sub_i32 s12, 0x80, s13
	s_min_i32 s38, s12, 8
	s_mul_i32 s5, s5, 40
	s_sub_i32 s4, s4, s5
	s_lshr_b32 s12, s4, 3
	s_and_b32 s4, s4, 7
	s_add_i32 s4, s13, s4
	s_and_b32 s52, s65, 1

.LBB0_1309:
	s_add_i32 s30, s30, 1
	s_mul_i32 s6, s30, s84
	s_mul_hi_u32 s7, s30, s33
	s_add_i32 s7, s7, s6
	s_mul_i32 s6, s30, s33
	s_add_u32 s6, s6, s2
	s_addc_u32 s7, s7, s85
	v_cmp_gt_i64_e32 vcc, s[6:7], v[186:187]
	v_cmp_lt_i64_e64 s[8:9], s[6:7], v[184:185]
	s_cbranch_vccnz .LBB0_1311
	s_ashr_i32 s7, s6, 31
	s_lshr_b32 s7, s7, 29
	s_add_i32 s7, s6, s7
	s_ashr_i32 s28, s7, 3
	s_and_b32 s7, s7, -8
	s_sub_i32 s6, s6, s7
	s_cmp_lt_i32 s6, 0
	s_movk_i32 s7, 0x71
	s_cselect_b32 s7, s7, 0x70
	s_mul_i32 s6, s6, s7
	s_add_i32 s6, s6, s28
	s_mul_hi_i32 s7, s6, 0x92492493
	s_add_i32 s7, s7, s6
	s_lshr_b32 s28, s7, 31
	s_ashr_i32 s7, s7, 5
	s_add_i32 s7, s7, s28
	s_lshl_b32 s29, s7, 3
	s_sub_i32 s28, 0x80, s29
	s_min_i32 s42, s28, 8
	s_mul_i32 s7, s7, 56
	s_sub_i32 s6, s6, s7
	s_lshr_b32 s28, s6, 3
	s_and_b32 s6, s6, 7
	s_add_i32 s67, s29, s6
	s_and_b32 s66, s30, 1
	s_cmp_lt_i32 s28, 3
	s_cselect_b32 s70, 0, 0x200
	s_cselect_b32 s29, 4, 2

.LBB0_1627:
	s_ashr_i32 s12, s14, 3
	s_add_i32 s12, s16, s12
	s_ashr_i32 s13, s12, 31
	s_lshr_b32 s13, s13, 27
	s_add_i32 s13, s12, s13
	s_ashr_i32 s14, s13, 5
	s_lshl_b32 s14, s14, 3
	s_sub_i32 s15, 0x80, s14
	s_min_i32 s15, s15, 8
	s_andn2_b32 s13, s13, 31
	s_sub_i32 s13, s12, s13
	s_lshr_b32 s12, s13, 3
	s_and_b32 s13, s13, 7
	s_add_i32 s14, s14, s13

.LBB0_1718:
	s_add_i32 s56, s56, 1
	s_mul_i32 s5, s56, s46
	s_mul_hi_u32 s6, s56, s33
	s_add_i32 s6, s6, s5
	s_mul_i32 s5, s56, s33
	s_add_u32 s14, s5, s2
	s_addc_u32 s15, s6, s3
	v_cmp_gt_i64_e32 vcc, s[14:15], v[146:147]
	v_cmp_lt_i64_e64 s[6:7], s[14:15], v[144:145]
	s_cbranch_vccnz .LBB0_1720
	s_ashr_i32 s4, s14, 31
	s_lshr_b32 s4, s4, 29
	s_add_i32 s4, s14, s4
	s_ashr_i32 s5, s4, 3
	s_and_b32 s4, s4, -8
	s_sub_i32 s4, s14, s4
	s_cmp_lt_i32 s4, 0
	s_cselect_b32 s12, s48, 0x160
	s_mul_i32 s4, s4, s12
	s_add_i32 s4, s4, s5
	s_mul_hi_i32 s5, s4, 0x2e8ba2e9
	s_lshr_b32 s12, s5, 31
	s_ashr_i32 s5, s5, 5
	s_add_i32 s5, s5, s12
	s_lshl_b32 s12, s5, 3
	s_sub_i32 s13, 0x80, s12
	s_min_i32 s13, s13, 8
	s_mulk_i32 s5, 0xb0
	s_sub_i32 s5, s4, s5
	s_lshr_b32 s4, s5, 3
	s_and_b32 s5, s5, 7
	s_add_i32 s12, s12, s5
	s_and_b32 s57, s56, 1

.LBB0_1821:
	s_ashr_i32 s0, s28, 3
	s_add_i32 s0, s34, s0
	s_ashr_i32 s1, s0, 31
	s_lshr_b32 s1, s1, 27
	s_add_i32 s1, s0, s1
	s_ashr_i32 s28, s1, 5
	s_lshl_b32 s28, s28, 3
	s_sub_i32 s29, 0x80, s28
	s_min_i32 s29, s29, 8
	s_andn2_b32 s1, s1, 31
	s_sub_i32 s0, s0, s1
	s_lshr_b32 s60, s0, 3
	s_and_b32 s0, s0, 7
	s_add_i32 s61, s28, s0
